# hgrn_out_task: intra-chunk loop issues its 8 K-fragment and 16 V-fragment loads at the top of the iteration (was one round trip per fragment); output epilogue issues its 16 gate + 16 gain loads up fro
# speedup vs baseline: 1.0106x; 1.0106x over previous
; DI f32x16 mfma32(bf16x8 a, bf16x8 b, f32x16 c) { return __builtin_amdgcn_mfma_f32_32x32x16_bf16(a, b, c, 0, 0, 0); }
; DI f32x16 zero16() { f32x16 z; for (int i = 0; i < 16; ++i) z[i] = 0.f; return z; }
; DI int crow(int i, int g) { return (i & 3) + 8 * (i >> 2) + 4 * g; }
; DI f32x16 score_tile(const bf16x8 (&qf)[8], const bf16_t* __restrict__ Kp  , unsigned koff  ) {
;   f32x16 acc = zero16();
;   const char* kr = (const char*)Kp;
; #pragma unroll
;   for (int ks = 0; ks < 8; ++ks) { const bf16x8 a = *(const bf16x8*)(kr + (size_t)(koff + ks * 32)); acc = mfma32(a, qf[ks], acc); }
;   return acc;
; }
; DI unsigned pk2h(float lo, float hi) { const f32x2 f = {lo, hi}; const hwbf16x2 r = __builtin_convertvector(f, hwbf16x2); return __builtin_bit_cast(unsigned, r); }
; DI bf16x8 pack8(const float* p) { u32x4 o; o.x = pk2h(p[0], p[1]); o.y = pk2h(p[2], p[3]); o.z = pk2h(p[4], p[5]); o.w = pk2h(p[6], p[7]); return __builtin_bit_cast(bf16x8, o); }
; DI void pv_tile(f32x16 (&o)[4], const bf16x8 (&pf)[2], const bf16_t* __restrict__ VTp  , size_t ldv, unsigned voff  ) {
; #pragma unroll
;   for (int vt = 0; vt < 4; ++vt) {
;     const char* vr = (const char*)(VTp + (size_t)(vt * 32) * ldv);
; #pragma unroll
;     for (int s = 0; s < 2; ++s) {
;       const s16x4 lo = *(const s16x4*)(vr + (size_t)(voff + 32 * s)), hi = *(const s16x4*)(vr + (size_t)(voff + 32 * s + 16));
;       const bf16x8 a = __builtin_shufflevector(lo, hi, 0, 1, 2, 3, 4, 5, 6, 7);
;       o[vt] = mfma32(a, pf[s], o[vt]);
;     }
;   }
; }
; DI void hgrn_out_task(const Params& p, int e, int bh, int c, int tt) {
;     ...
;   for (int st = 0; st <= tt; ++st) {
;     f32x16 acc = score_tile(qf, KT + (size_t)st * 32 * 128, koff);
;     float a[16];
; #pragma unroll
;     for (int i = 0; i < 16; ++i) a[i] = (st < tt || crow(i, g) <= lr) ? acc[i] : 0.f;
;     bf16x8 pf[2]; pf[0] = pack8(a); pf[1] = pack8(a + 8);
;     pv_tile(o, pf, VT + (size_t)st * 4096, 32, voffT);
;   }
.LBB0_283:
	v_lshl_add_u64 v[140:141], v[130:131], 0, s[56:57]
	v_lshl_add_u64 v[216:217], v[134:135], 0, s[56:57]
	s_mov_b64 s[34:35], 0x2b145000
	v_lshl_add_u64 v[218:219], v[216:217], 0, s[34:35]
	s_mov_b64 s[34:35], 0x2b146000
	v_lshl_add_u64 v[216:217], v[216:217], 0, s[34:35]
	v_lshl_add_u64 v[220:221], v[132:133], 0, s[56:57]
	global_load_dwordx4 v[142:145], v[140:141], off offset:-128
	global_load_dwordx4 v[146:149], v[140:141], off offset:-96
	global_load_dwordx4 v[150:153], v[140:141], off offset:-64
	global_load_dwordx4 v[154:157], v[140:141], off offset:-32
	global_load_dwordx4 v[158:161], v[140:141], off
	global_load_dwordx4 v[162:165], v[140:141], off offset:32
	global_load_dwordx4 v[166:169], v[140:141], off offset:64
	global_load_dwordx4 v[170:173], v[140:141], off offset:96
	global_load_dwordx2 v[174:175], v[218:219], off
	global_load_dwordx2 v[176:177], v[218:219], off offset:16
	global_load_dwordx2 v[178:179], v[218:219], off offset:32
	global_load_dwordx2 v[180:181], v[218:219], off offset:48
	global_load_dwordx2 v[182:183], v[218:219], off offset:2048
	global_load_dwordx2 v[184:185], v[218:219], off offset:2064
	global_load_dwordx2 v[186:187], v[218:219], off offset:2080
	global_load_dwordx2 v[188:189], v[218:219], off offset:2096
	global_load_dwordx2 v[200:201], v[216:217], off
	global_load_dwordx2 v[202:203], v[216:217], off offset:16
	global_load_dwordx2 v[204:205], v[220:221], off offset:-2048
	global_load_dwordx2 v[206:207], v[220:221], off offset:-2032
	global_load_dwordx2 v[208:209], v[216:217], off offset:2048
	global_load_dwordx2 v[210:211], v[216:217], off offset:2064
	global_load_dwordx2 v[212:213], v[220:221], off
	global_load_dwordx2 v[214:215], v[220:221], off offset:16
	v_cmp_lt_u32_e64 s[34:35], s33, v119
	s_or_b64 s[36:37], s[34:35], vcc
	s_add_i32 s33, s33, 1
	s_waitcnt vmcnt(23)
	v_mfma_f32_32x32x16_bf16 v[66:81], v[142:145], v[82:85], 0
	s_waitcnt vmcnt(22)
	v_mfma_f32_32x32x16_bf16 v[66:81], v[146:149], v[86:89], v[66:81]
	s_waitcnt vmcnt(21)
	v_mfma_f32_32x32x16_bf16 v[66:81], v[150:153], v[90:93], v[66:81]
	s_waitcnt vmcnt(20)
	v_mfma_f32_32x32x16_bf16 v[66:81], v[154:157], v[94:97], v[66:81]
	s_waitcnt vmcnt(19)
	v_mfma_f32_32x32x16_bf16 v[66:81], v[158:161], v[98:101], v[66:81]
	s_waitcnt vmcnt(18)
	v_mfma_f32_32x32x16_bf16 v[66:81], v[162:165], v[102:105], v[66:81]
	s_waitcnt vmcnt(17)
	v_mfma_f32_32x32x16_bf16 v[66:81], v[166:169], v[106:109], v[66:81]
	s_waitcnt vmcnt(16)
	v_mfma_f32_32x32x16_bf16 v[66:81], v[170:173], v[110:113], v[66:81]
	s_nop 11
	v_cndmask_b32_e64 v0, 0, v66, s[36:37]
	s_or_b64 s[36:37], s[34:35], s[0:1]
	v_cndmask_b32_e64 v66, 0, v67, s[36:37]
	s_or_b64 s[36:37], s[34:35], s[30:31]
	v_cndmask_b32_e64 v67, 0, v68, s[36:37]
	s_or_b64 s[36:37], s[34:35], s[4:5]
	v_cndmask_b32_e64 v68, 0, v69, s[36:37]
	s_or_b64 s[36:37], s[34:35], s[6:7]
	v_cndmask_b32_e64 v69, 0, v70, s[36:37]
	s_or_b64 s[36:37], s[34:35], s[8:9]
	v_cndmask_b32_e64 v127, 0, v71, s[36:37]
	s_or_b64 s[36:37], s[34:35], s[10:11]
	v_cndmask_b32_e64 v136, 0, v72, s[36:37]
	s_or_b64 s[36:37], s[34:35], s[12:13]
	v_cndmask_b32_e64 v73, 0, v73, s[36:37]
	s_or_b64 s[36:37], s[34:35], s[14:15]
	v_cndmask_b32_e64 v74, 0, v74, s[36:37]
	s_or_b64 s[36:37], s[34:35], s[16:17]
	v_cndmask_b32_e64 v75, 0, v75, s[36:37]
	s_or_b64 s[36:37], s[34:35], s[18:19]
	v_cndmask_b32_e64 v76, 0, v76, s[36:37]
	s_or_b64 s[36:37], s[34:35], s[20:21]
	v_cndmask_b32_e64 v77, 0, v77, s[36:37]
	s_or_b64 s[36:37], s[34:35], s[22:23]
	v_cndmask_b32_e64 v78, 0, v78, s[36:37]
	s_or_b64 s[36:37], s[34:35], s[24:25]
	v_cndmask_b32_e64 v79, 0, v79, s[36:37]
	s_or_b64 s[36:37], s[34:35], s[26:27]
	s_or_b64 s[34:35], s[34:35], s[28:29]
	v_cndmask_b32_e64 v80, 0, v80, s[36:37]
	v_cndmask_b32_e64 v81, 0, v81, s[34:35]
	v_cvt_pk_bf16_f32 v70, v0, v66
	v_cvt_pk_bf16_f32 v66, v74, v75
	v_cvt_pk_bf16_f32 v72, v69, v127
	v_cvt_pk_bf16_f32 v69, v80, v81
	v_cvt_pk_bf16_f32 v71, v67, v68
	v_cvt_pk_bf16_f32 v67, v76, v77
	v_cvt_pk_bf16_f32 v68, v78, v79
	v_cvt_pk_bf16_f32 v73, v136, v73
	s_nop 1
	s_waitcnt vmcnt(14)
	v_mfma_f32_32x32x16_bf16 v[50:65], v[174:177], v[70:73], v[50:65]
	s_waitcnt vmcnt(12)
	v_mfma_f32_32x32x16_bf16 v[50:65], v[178:181], v[66:69], v[50:65]
	s_waitcnt vmcnt(10)
	v_mfma_f32_32x32x16_bf16 v[34:49], v[182:185], v[70:73], v[34:49]
	s_waitcnt vmcnt(8)
	v_mfma_f32_32x32x16_bf16 v[34:49], v[186:189], v[66:69], v[34:49]
	s_waitcnt vmcnt(6)
	v_mfma_f32_32x32x16_bf16 v[18:33], v[200:203], v[70:73], v[18:33]
	s_waitcnt vmcnt(4)
	v_mfma_f32_32x32x16_bf16 v[18:33], v[204:207], v[66:69], v[18:33]
	s_waitcnt vmcnt(2)
	v_mfma_f32_32x32x16_bf16 v[2:17], v[208:211], v[70:73], v[2:17]
	s_waitcnt vmcnt(0)
	v_mfma_f32_32x32x16_bf16 v[2:17], v[212:215], v[66:69], v[2:17]
	s_add_u32 s56, s56, 0x2000
	s_addc_u32 s57, s57, 0
	v_cmp_eq_u32_e64 s[34:35], s56, v116
	s_or_b64 s[54:55], s[34:35], s[54:55]
	s_andn2_b64 exec, exec, s[54:55]
	s_cbranch_execnz .LBB0_283
; DI f32x16 mfma32(bf16x8 a, bf16x8 b, f32x16 c) { return __builtin_amdgcn_mfma_f32_32x32x16_bf16(a, b, c, 0, 0, 0); }
; DI void hgrn_out_task(const Params& p, int e, int bh, int c, int tt) {
;     ...
;   load_q_raw(qf, QS + (size_t)(tt * 32 + lr) * 128, g);
; #pragma unroll
;   for (int vt = 0; vt < 4; ++vt) {
;     const bf16_t* sr = ST + (size_t)(vt * 32 + lr) * 128 + g * 8;
; #pragma unroll
;     for (int ks = 0; ks < 8; ++ks) { const bf16x8 a = *(const bf16x8*)(sr + ks * 16); o[vt] = mfma32(a, qf[ks], o[vt]); }
;   }
;   float ss = 0.f;
; #pragma unroll
;   for (int vt = 0; vt < 4; ++vt)
; #pragma unroll
;     for (int i = 0; i < 16; ++i) ss += o[vt][i] * o[vt][i];
	s_or_b64 exec, exec, s[54:55]
	v_lshlrev_b64 v[66:67], 21, v[122:123]
	v_lshl_add_u64 v[66:67], s[40:41], 0, v[66:67]
	v_lshlrev_b32_e32 v0, 15, v121
	v_lshl_add_u64 v[68:69], v[128:129], 1, s[42:43]
	v_lshl_add_u64 v[100:101], v[66:67], 0, v[0:1]
	v_lshlrev_b32_e32 v0, 1, v126
	v_lshl_add_u64 v[66:67], v[68:69], 0, v[0:1]
	v_lshlrev_b32_e32 v0, 1, v124
	v_lshl_add_u64 v[100:101], v[100:101], 0, v[0:1]
	v_mov_b32_e32 v121, v1
	v_lshl_add_u64 v[66:67], v[66:67], 0, v[0:1]
	v_lshl_add_u64 v[100:101], v[100:101], 0, v[120:121]
	global_load_dwordx4 v[94:97], v[66:67], off
	global_load_dwordx4 v[90:93], v[66:67], off offset:32
	global_load_dwordx4 v[86:89], v[66:67], off offset:64
	global_load_dwordx4 v[82:85], v[66:67], off offset:96
	global_load_dwordx4 v[78:81], v[66:67], off offset:128
	global_load_dwordx4 v[74:77], v[66:67], off offset:160
	global_load_dwordx4 v[70:73], v[66:67], off offset:192
	s_nop 0
	global_load_dwordx4 v[66:69], v[66:67], off offset:224
	v_ashrrev_i32_e32 v98, 10, v115
	v_ashrrev_i32_e32 v99, 31, v98
	v_readlane_b32 s34, v253, 48
	v_readlane_b32 s35, v253, 49
	s_mov_b64 s[0:1], 0x23081800
	v_add_co_u32_e32 v216, vcc, 0x2000, v100
	s_nop 1
	v_addc_co_u32_e32 v217, vcc, 0, v101, vcc
	v_add_co_u32_e32 v218, vcc, 0x4000, v100
	s_nop 1
	v_addc_co_u32_e32 v219, vcc, 0, v101, vcc
	v_add_co_u32_e32 v220, vcc, 0x6000, v100
	s_nop 1
	v_addc_co_u32_e32 v221, vcc, 0, v101, vcc
	global_load_dwordx4 v[142:145], v[100:101], off
	global_load_dwordx4 v[146:149], v[100:101], off offset:32
	global_load_dwordx4 v[150:153], v[100:101], off offset:64
	global_load_dwordx4 v[154:157], v[100:101], off offset:96
	global_load_dwordx4 v[158:161], v[100:101], off offset:128
	global_load_dwordx4 v[162:165], v[100:101], off offset:160
	global_load_dwordx4 v[166:169], v[100:101], off offset:192
	global_load_dwordx4 v[170:173], v[100:101], off offset:224
	global_load_dwordx4 v[174:177], v[216:217], off
	global_load_dwordx4 v[178:181], v[216:217], off offset:32
	global_load_dwordx4 v[182:185], v[216:217], off offset:64
	global_load_dwordx4 v[186:189], v[216:217], off offset:96
	global_load_dwordx4 v[200:203], v[216:217], off offset:128
	global_load_dwordx4 v[204:207], v[216:217], off offset:160
	global_load_dwordx4 v[208:211], v[216:217], off offset:192
	global_load_dwordx4 v[212:215], v[216:217], off offset:224
	s_waitcnt vmcnt(15)
	v_mfma_f32_32x32x16_bf16 v[50:65], v[142:145], v[94:97], v[50:65]
	s_waitcnt vmcnt(14)
	v_mfma_f32_32x32x16_bf16 v[50:65], v[146:149], v[90:93], v[50:65]
	s_waitcnt vmcnt(13)
	v_mfma_f32_32x32x16_bf16 v[50:65], v[150:153], v[86:89], v[50:65]
	s_waitcnt vmcnt(12)
	v_mfma_f32_32x32x16_bf16 v[50:65], v[154:157], v[82:85], v[50:65]
	s_waitcnt vmcnt(11)
	v_mfma_f32_32x32x16_bf16 v[50:65], v[158:161], v[78:81], v[50:65]
	s_waitcnt vmcnt(10)
	v_mfma_f32_32x32x16_bf16 v[50:65], v[162:165], v[74:77], v[50:65]
	s_waitcnt vmcnt(9)
	v_mfma_f32_32x32x16_bf16 v[50:65], v[166:169], v[70:73], v[50:65]
	s_waitcnt vmcnt(8)
	v_mfma_f32_32x32x16_bf16 v[50:65], v[170:173], v[66:69], v[50:65]
	global_load_dwordx4 v[142:145], v[218:219], off
	global_load_dwordx4 v[146:149], v[218:219], off offset:32
	global_load_dwordx4 v[150:153], v[218:219], off offset:64
	global_load_dwordx4 v[154:157], v[218:219], off offset:96
	global_load_dwordx4 v[158:161], v[218:219], off offset:128
	global_load_dwordx4 v[162:165], v[218:219], off offset:160
	global_load_dwordx4 v[166:169], v[218:219], off offset:192
	global_load_dwordx4 v[170:173], v[218:219], off offset:224
	s_nop 3
	v_mul_f32_e32 v0, v51, v51
	v_fmac_f32_e32 v0, v50, v50
	v_fmac_f32_e32 v0, v52, v52
	v_fmac_f32_e32 v0, v53, v53
	v_fmac_f32_e32 v0, v54, v54
	v_fmac_f32_e32 v0, v55, v55
	v_fmac_f32_e32 v0, v56, v56
	v_fmac_f32_e32 v0, v57, v57
	v_fmac_f32_e32 v0, v58, v58
	v_fmac_f32_e32 v0, v59, v59
	v_fmac_f32_e32 v0, v60, v60
	v_fmac_f32_e32 v0, v61, v61
	v_fmac_f32_e32 v0, v62, v62
	v_fmac_f32_e32 v0, v63, v63
	v_fmac_f32_e32 v0, v64, v64
	v_fmac_f32_e32 v0, v65, v65
	s_waitcnt vmcnt(15)
	v_mfma_f32_32x32x16_bf16 v[34:49], v[174:177], v[94:97], v[34:49]
	s_waitcnt vmcnt(14)
	v_mfma_f32_32x32x16_bf16 v[34:49], v[178:181], v[90:93], v[34:49]
	s_waitcnt vmcnt(13)
	v_mfma_f32_32x32x16_bf16 v[34:49], v[182:185], v[86:89], v[34:49]
	s_waitcnt vmcnt(12)
	v_mfma_f32_32x32x16_bf16 v[34:49], v[186:189], v[82:85], v[34:49]
	s_waitcnt vmcnt(11)
	v_mfma_f32_32x32x16_bf16 v[34:49], v[200:203], v[78:81], v[34:49]
	s_waitcnt vmcnt(10)
	v_mfma_f32_32x32x16_bf16 v[34:49], v[204:207], v[74:77], v[34:49]
	s_waitcnt vmcnt(9)
	v_mfma_f32_32x32x16_bf16 v[34:49], v[208:211], v[70:73], v[34:49]
	s_waitcnt vmcnt(8)
	v_mfma_f32_32x32x16_bf16 v[34:49], v[212:215], v[66:69], v[34:49]
	global_load_dwordx4 v[174:177], v[220:221], off
	global_load_dwordx4 v[178:181], v[220:221], off offset:32
	global_load_dwordx4 v[182:185], v[220:221], off offset:64
	global_load_dwordx4 v[186:189], v[220:221], off offset:96
	global_load_dwordx4 v[200:203], v[220:221], off offset:128
	global_load_dwordx4 v[204:207], v[220:221], off offset:160
	global_load_dwordx4 v[208:211], v[220:221], off offset:192
	global_load_dwordx4 v[212:215], v[220:221], off offset:224
	s_nop 3
	v_fmac_f32_e32 v0, v34, v34
	v_fmac_f32_e32 v0, v35, v35
	v_fmac_f32_e32 v0, v36, v36
	v_fmac_f32_e32 v0, v37, v37
	v_fmac_f32_e32 v0, v38, v38
	v_fmac_f32_e32 v0, v39, v39
	v_fmac_f32_e32 v0, v40, v40
	v_fmac_f32_e32 v0, v41, v41
	v_fmac_f32_e32 v0, v42, v42
	v_fmac_f32_e32 v0, v43, v43
	v_fmac_f32_e32 v0, v44, v44
	v_fmac_f32_e32 v0, v45, v45
	v_fmac_f32_e32 v0, v46, v46
	v_fmac_f32_e32 v0, v47, v47
	v_fmac_f32_e32 v0, v48, v48
	v_fmac_f32_e32 v0, v49, v49
	s_waitcnt vmcnt(15)
; DI float bf2f(bf16_t v) { return __uint_as_float(((unsigned)v) << 16); }
; DI float xhalf_sum(float v) { const auto r = __builtin_amdgcn_permlane32_swap(__float_as_uint(v), __float_as_uint(v), false, false); return __uint_as_float(r[0]) + __uint_as_float(r[1]); }
; DI float frcp(float x) { return __builtin_amdgcn_rcpf(x); }
; DI f32x16 mfma32(bf16x8 a, bf16x8 b, f32x16 c) { return __builtin_amdgcn_mfma_f32_32x32x16_bf16(a, b, c, 0, 0, 0); }
; DI void st_bf16x4(bf16_t* p, f32x4 v) { u32x2 o; o.x = pk2e(v[0], v[1]); o.y = pk2e(v[2], v[3]); *(u32x2*)p = o; }
; DI void hgrn_out_task(const Params& p, int e, int bh, int c, int tt) {
;     ...
;   for (int vt = 0; vt < 4; ++vt) {
;     const bf16_t* sr = ST + (size_t)(vt * 32 + lr) * 128 + g * 8;
; #pragma unroll
;     for (int ks = 0; ks < 8; ++ks) { const bf16x8 a = *(const bf16x8*)(sr + ks * 16); o[vt] = mfma32(a, qf[ks], o[vt]); }
;   }
;   float ss = 0.f;
; #pragma unroll
;   for (int vt = 0; vt < 4; ++vt)
; #pragma unroll
;     for (int i = 0; i < 16; ++i) ss += o[vt][i] * o[vt][i];
;   ss = xhalf_sum(ss);
;   const float rs = rsqrtf(ss * (1.f / 128.f) + EPS_);
;   const size_t m = (size_t)b * T_ + c * 64 + tt * 32 + lr;
;   const bf16_t* hg = (const bf16_t*)(p.ws + E_HG) + m * 1024 + h * 128;
;   const float* og = p.in[12] + e * 128;
;   bf16_t* orow = (bf16_t*)(p.ws + A_MIXO) + m * D_ + 1024 + h * 128;
; #pragma unroll
;   for (int vt = 0; vt < 4; ++vt)
; #pragma unroll
;     for (int q = 0; q < 4; ++q) {
;       const int d0 = vt * 32 + q * 8 + 4 * g;
;       const s16x4 gv = *(const s16x4*)(hg + d0); const f32x4 gn = *(const f32x4*)(og + d0);
;       f32x4 v;
; #pragma unroll
;       for (int e2 = 0; e2 < 4; ++e2) { const float gg = bf2f((bf16_t)gv[e2]); v[e2] = o[vt][q * 4 + e2] * rs * gn[e2] * (gg * frcp(1.f + __expf(-gg))); }
;       st_bf16x4(orow + d0, v);
	v_mfma_f32_32x32x16_bf16 v[18:33], v[142:145], v[94:97], v[18:33]
	s_waitcnt vmcnt(14)
	v_mfma_f32_32x32x16_bf16 v[18:33], v[146:149], v[90:93], v[18:33]
	s_waitcnt vmcnt(13)
	v_mfma_f32_32x32x16_bf16 v[18:33], v[150:153], v[86:89], v[18:33]
	s_waitcnt vmcnt(12)
	v_mfma_f32_32x32x16_bf16 v[18:33], v[154:157], v[82:85], v[18:33]
	s_waitcnt vmcnt(11)
	v_mfma_f32_32x32x16_bf16 v[18:33], v[158:161], v[78:81], v[18:33]
	s_waitcnt vmcnt(10)
	v_mfma_f32_32x32x16_bf16 v[18:33], v[162:165], v[74:77], v[18:33]
	s_waitcnt vmcnt(9)
	v_mfma_f32_32x32x16_bf16 v[18:33], v[166:169], v[70:73], v[18:33]
	s_waitcnt vmcnt(8)
	v_mfma_f32_32x32x16_bf16 v[18:33], v[170:173], v[66:69], v[18:33]
	s_waitcnt vmcnt(7)
	v_mfma_f32_32x32x16_bf16 v[2:17], v[174:177], v[94:97], v[2:17]
	s_waitcnt vmcnt(6)
	v_mfma_f32_32x32x16_bf16 v[2:17], v[178:181], v[90:93], v[2:17]
	s_waitcnt vmcnt(5)
	v_mfma_f32_32x32x16_bf16 v[2:17], v[182:185], v[86:89], v[2:17]
	s_waitcnt vmcnt(4)
	v_mfma_f32_32x32x16_bf16 v[2:17], v[186:189], v[82:85], v[2:17]
	s_waitcnt vmcnt(3)
	v_mfma_f32_32x32x16_bf16 v[2:17], v[200:203], v[78:81], v[2:17]
	s_waitcnt vmcnt(2)
	v_mfma_f32_32x32x16_bf16 v[2:17], v[204:207], v[74:77], v[2:17]
	s_waitcnt vmcnt(1)
	v_mfma_f32_32x32x16_bf16 v[2:17], v[208:211], v[70:73], v[2:17]
	s_waitcnt vmcnt(0)
	v_mfma_f32_32x32x16_bf16 v[2:17], v[212:215], v[66:69], v[2:17]
	v_fmac_f32_e32 v0, v18, v18
	v_fmac_f32_e32 v0, v19, v19
	v_fmac_f32_e32 v0, v20, v20
	v_fmac_f32_e32 v0, v21, v21
	v_fmac_f32_e32 v0, v22, v22
	v_fmac_f32_e32 v0, v23, v23
	v_fmac_f32_e32 v0, v24, v24
	v_fmac_f32_e32 v0, v25, v25
	v_fmac_f32_e32 v0, v26, v26
	v_fmac_f32_e32 v0, v27, v27
	v_fmac_f32_e32 v0, v28, v28
	v_fmac_f32_e32 v0, v29, v29
	v_fmac_f32_e32 v0, v30, v30
	v_fmac_f32_e32 v0, v31, v31
	v_fmac_f32_e32 v0, v32, v32
	v_fmac_f32_e32 v0, v33, v33
	s_nop 11
	v_fmac_f32_e32 v0, v2, v2
	v_fmac_f32_e32 v0, v3, v3
	v_fmac_f32_e32 v0, v4, v4
	v_fmac_f32_e32 v0, v5, v5
	v_fmac_f32_e32 v0, v6, v6
	v_fmac_f32_e32 v0, v7, v7
	v_fmac_f32_e32 v0, v8, v8
	v_fmac_f32_e32 v0, v9, v9
	v_fmac_f32_e32 v0, v10, v10
	v_fmac_f32_e32 v0, v11, v11
	v_pk_mul_f32 v[70:71], v[12:13], v[12:13]
	v_pk_mul_f32 v[68:69], v[14:15], v[14:15]
	v_add_f32_e32 v0, v70, v0
	v_add_f32_e32 v0, v71, v0
	v_add_f32_e32 v0, v68, v0
	v_pk_mul_f32 v[66:67], v[16:17], v[16:17]
	v_add_f32_e32 v0, v69, v0
	v_add_f32_e32 v0, v66, v0
	v_add_f32_e32 v0, v67, v0
	v_mov_b32_e32 v66, v0
	s_nop 1
	v_permlane32_swap_b32_e32 v0, v66
	v_add_f32_e32 v0, v0, v66
	v_fmamk_f32 v0, v0, 0x3c000000, v249
	v_cmp_gt_f32_e32 vcc, s84, v0
	v_mul_f32_e32 v66, 0x4b800000, v0
	v_lshlrev_b32_e32 v71, 2, v117
	v_cndmask_b32_e32 v0, v0, v66, vcc
	v_rsq_f32_e32 v0, v0
	s_nop 0
	v_mul_f32_e32 v66, 0x45800000, v0
	v_cndmask_b32_e32 v70, v0, v66, vcc
	v_lshlrev_b64 v[66:67], 12, v[98:99]
	v_or_b32_e32 v0, v66, v114
	v_or_b32_e32 v0, v0, v125
	v_or_b32_e32 v66, v0, v118
	v_lshlrev_b64 v[68:69], 11, v[66:67]
	v_and_b32_e32 v0, 0x380, v115
	v_lshlrev_b64 v[66:67], 12, v[66:67]
	v_lshl_add_u64 v[68:69], s[44:45], 0, v[68:69]
	v_lshlrev_b32_e32 v0, 1, v0
	v_lshl_add_u64 v[66:67], s[34:35], 0, v[66:67]
	v_lshl_add_u64 v[68:69], v[68:69], 0, v[0:1]
	v_lshl_add_u64 v[74:75], v[66:67], 0, v[0:1]
	v_lshlrev_b32_e32 v0, 1, v117
	v_lshl_add_u64 v[72:73], v[68:69], 0, v[0:1]
	global_load_dwordx2 v[216:217], v[72:73], off
	global_load_dwordx4 v[142:145], v71, s[46:47]
	global_load_dwordx2 v[218:219], v[72:73], off offset:16
	global_load_dwordx4 v[146:149], v71, s[46:47] offset:32
	global_load_dwordx2 v[220:221], v[72:73], off offset:32
	global_load_dwordx4 v[150:153], v71, s[46:47] offset:64
	global_load_dwordx2 v[222:223], v[72:73], off offset:48
	global_load_dwordx4 v[154:157], v71, s[46:47] offset:96
	global_load_dwordx2 v[224:225], v[72:73], off offset:64
	global_load_dwordx4 v[158:161], v71, s[46:47] offset:128
	global_load_dwordx2 v[226:227], v[72:73], off offset:80
	global_load_dwordx4 v[162:165], v71, s[46:47] offset:160
	global_load_dwordx2 v[228:229], v[72:73], off offset:96
	global_load_dwordx4 v[166:169], v71, s[46:47] offset:192
	global_load_dwordx2 v[230:231], v[72:73], off offset:112
	global_load_dwordx4 v[170:173], v71, s[46:47] offset:224
	global_load_dwordx2 v[232:233], v[72:73], off offset:128
	global_load_dwordx4 v[174:177], v71, s[46:47] offset:256
	global_load_dwordx2 v[234:235], v[72:73], off offset:144
	global_load_dwordx4 v[178:181], v71, s[46:47] offset:288
	global_load_dwordx2 v[236:237], v[72:73], off offset:160
	global_load_dwordx4 v[182:185], v71, s[46:47] offset:320
	global_load_dwordx2 v[238:239], v[72:73], off offset:176
	global_load_dwordx4 v[186:189], v71, s[46:47] offset:352
	global_load_dwordx2 v[240:241], v[72:73], off offset:192
	global_load_dwordx4 v[200:203], v71, s[46:47] offset:384
	global_load_dwordx2 v[242:243], v[72:73], off offset:208
	global_load_dwordx4 v[204:207], v71, s[46:47] offset:416
	global_load_dwordx2 v[244:245], v[72:73], off offset:224
	global_load_dwordx4 v[208:211], v71, s[46:47] offset:448
	global_load_dwordx2 v[246:247], v[72:73], off offset:240
	global_load_dwordx4 v[212:215], v71, s[46:47] offset:480
	v_pk_mul_f32 v[50:51], v[50:51], v[70:71] op_sel_hi:[1,0]
	v_pk_mul_f32 v[52:53], v[52:53], v[70:71] op_sel_hi:[1,0]
	v_pk_mul_f32 v[54:55], v[54:55], v[70:71] op_sel_hi:[1,0]
	v_pk_mul_f32 v[56:57], v[56:57], v[70:71] op_sel_hi:[1,0]
	v_pk_mul_f32 v[58:59], v[58:59], v[70:71] op_sel_hi:[1,0]
	v_pk_mul_f32 v[60:61], v[60:61], v[70:71] op_sel_hi:[1,0]
	v_pk_mul_f32 v[62:63], v[62:63], v[70:71] op_sel_hi:[1,0]
	v_pk_mul_f32 v[34:35], v[34:35], v[70:71] op_sel_hi:[1,0]
	v_pk_mul_f32 v[36:37], v[36:37], v[70:71] op_sel_hi:[1,0]
	v_pk_mul_f32 v[38:39], v[38:39], v[70:71] op_sel_hi:[1,0]
	v_pk_mul_f32 v[40:41], v[40:41], v[70:71] op_sel_hi:[1,0]
	v_pk_mul_f32 v[42:43], v[42:43], v[70:71] op_sel_hi:[1,0]
	v_pk_mul_f32 v[18:19], v[18:19], v[70:71] op_sel_hi:[1,0]
	v_pk_mul_f32 v[20:21], v[20:21], v[70:71] op_sel_hi:[1,0]
	v_pk_mul_f32 v[22:23], v[22:23], v[70:71] op_sel_hi:[1,0]
	v_pk_mul_f32 v[24:25], v[24:25], v[70:71] op_sel_hi:[1,0]
	v_pk_mul_f32 v[26:27], v[26:27], v[70:71] op_sel_hi:[1,0]
	v_pk_mul_f32 v[2:3], v[2:3], v[70:71] op_sel_hi:[1,0]
	v_pk_mul_f32 v[4:5], v[4:5], v[70:71] op_sel_hi:[1,0]
	v_pk_mul_f32 v[6:7], v[6:7], v[70:71] op_sel_hi:[1,0]
	v_pk_mul_f32 v[8:9], v[8:9], v[70:71] op_sel_hi:[1,0]
	v_pk_mul_f32 v[10:11], v[10:11], v[70:71] op_sel_hi:[1,0]
	s_waitcnt vmcnt(31)
; #define TIDX launder((int)threadIdx.x)
; DI float bf2f(bf16_t v) { return __uint_as_float(((unsigned)v) << 16); }
; DI float frcp(float x) { return __builtin_amdgcn_rcpf(x); }
; DI void st_bf16x4(bf16_t* p, f32x4 v) { u32x2 o; o.x = pk2e(v[0], v[1]); o.y = pk2e(v[2], v[3]); *(u32x2*)p = o; }
; DI void hgrn_out_task(const Params& p, int e, int bh, int c, int tt) {
;     ...
; #pragma unroll
;   for (int vt = 0; vt < 4; ++vt)
; #pragma unroll
;     for (int q = 0; q < 4; ++q) {
;       const int d0 = vt * 32 + q * 8 + 4 * g;
;       const s16x4 gv = *(const s16x4*)(hg + d0); const f32x4 gn = *(const f32x4*)(og + d0);
;       f32x4 v;
; #pragma unroll
;       for (int e2 = 0; e2 < 4; ++e2) { const float gg = bf2f((bf16_t)gv[e2]); v[e2] = o[vt][q * 4 + e2] * rs * gn[e2] * (gg * frcp(1.f + __expf(-gg))); }
;       st_bf16x4(orow + d0, v);
; DI void run_phase(const Params& p0, int ph) {
;     ...
;         if (KEYOK(9)) { const int wave = TIDX >> 6; for (int ti = wave * gridDim.x + blockIdx.x; ti < 2048; ti += 8 * gridDim.x) hgrn_out_task(p, e, ti >> 7, (ti >> 1) & 63, ti & 1); }
	v_and_b32_e32 v79, 0xffff0000, v216
	v_lshlrev_b32_e32 v78, 16, v216
	v_mul_f32_e32 v76, 0xbfb8aa3b, v78
	s_waitcnt vmcnt(30)
	v_pk_mul_f32 v[50:51], v[142:143], v[50:51]
	v_mul_f32_e32 v66, 0xbfb8aa3b, v79
	v_exp_f32_e32 v76, v76
	v_exp_f32_e32 v66, v66
	v_pk_mul_f32 v[52:53], v[144:145], v[52:53]
	v_add_f32_e32 v76, 1.0, v76
	v_add_f32_e32 v66, 1.0, v66
	v_rcp_f32_e32 v80, v76
	v_rcp_f32_e32 v81, v66
	s_nop 0
	v_pk_mul_f32 v[66:67], v[80:81], v[78:79]
	s_nop 0
	v_pk_mul_f32 v[66:67], v[66:67], v[50:51]
	v_and_b32_e32 v51, 0xffff0000, v217
	v_lshlrev_b32_e32 v50, 16, v217
	v_mul_f32_e32 v76, 0xbfb8aa3b, v50
	v_mul_f32_e32 v68, 0xbfb8aa3b, v51
	v_exp_f32_e32 v76, v76
	v_exp_f32_e32 v68, v68
	v_cvt_pk_bf16_f32 v66, v66, v67
	v_add_f32_e32 v76, 1.0, v76
	v_add_f32_e32 v68, 1.0, v68
	v_rcp_f32_e32 v76, v76
	v_rcp_f32_e32 v77, v68
	v_lshl_add_u64 v[68:69], v[74:75], 0, v[0:1]
	v_pk_mul_f32 v[50:51], v[76:77], v[50:51]
	s_nop 0
	v_pk_mul_f32 v[52:53], v[50:51], v[52:53]
	v_lshl_add_u64 v[50:51], v[68:69], 0, s[0:1]
	s_mov_b32 s0, 0x23081000
	v_cvt_pk_bf16_f32 v67, v52, v53
	v_add_co_u32_e32 v52, vcc, s0, v68
	v_readlane_b32 s0, v252, 43
	s_nop 0
	v_addc_co_u32_e32 v53, vcc, 0, v69, vcc
	global_store_dwordx2 v[52:53], v[66:67], off offset:2048
	s_nop 0
	v_add_u32_e32 v115, s0, v115
	s_movk_i32 s0, 0x7ff
	v_cmp_lt_i32_e32 vcc, s0, v115
	s_or_b64 s[52:53], vcc, s[52:53]
	v_readlane_b32 s1, v252, 44
	s_waitcnt vmcnt(30)
	v_lshlrev_b32_e32 v74, 16, v218
	v_mul_f32_e32 v0, 0xbfb8aa3b, v74
	v_exp_f32_e32 v0, v0
	v_and_b32_e32 v75, 0xffff0000, v218
	s_waitcnt vmcnt(29)
	v_pk_mul_f32 v[54:55], v[146:147], v[54:55]
	v_pk_mul_f32 v[56:57], v[148:149], v[56:57]
	v_add_f32_e32 v0, 1.0, v0
	v_rcp_f32_e32 v76, v0
	v_mul_f32_e32 v0, 0xbfb8aa3b, v75
	v_exp_f32_e32 v0, v0
	s_nop 0
	v_add_f32_e32 v0, 1.0, v0
	v_rcp_f32_e32 v77, v0
	s_nop 0
	v_pk_mul_f32 v[66:67], v[76:77], v[74:75]
	s_nop 0
	v_pk_mul_f32 v[54:55], v[54:55], v[66:67]
	v_lshlrev_b32_e32 v66, 16, v219
	v_mul_f32_e32 v0, 0xbfb8aa3b, v66
	v_exp_f32_e32 v0, v0
	v_and_b32_e32 v67, 0xffff0000, v219
	v_cvt_pk_bf16_f32 v54, v54, v55
	v_add_f32_e32 v0, 1.0, v0
	v_rcp_f32_e32 v52, v0
	v_mul_f32_e32 v0, 0xbfb8aa3b, v67
	v_exp_f32_e32 v0, v0
	s_nop 0
	v_add_f32_e32 v0, 1.0, v0
	v_rcp_f32_e32 v53, v0
	s_nop 0
	v_pk_mul_f32 v[52:53], v[52:53], v[66:67]
	s_nop 0
	v_pk_mul_f32 v[52:53], v[56:57], v[52:53]
	s_nop 0
	v_cvt_pk_bf16_f32 v55, v52, v53
	global_store_dwordx2 v[50:51], v[54:55], off offset:16
	s_nop 0
	s_waitcnt vmcnt(29)
	v_lshlrev_b32_e32 v66, 16, v220
	v_mul_f32_e32 v0, 0xbfb8aa3b, v66
	v_exp_f32_e32 v0, v0
	v_and_b32_e32 v67, 0xffff0000, v220
	s_waitcnt vmcnt(28)
	v_pk_mul_f32 v[52:53], v[150:151], v[58:59]
	v_pk_mul_f32 v[54:55], v[152:153], v[60:61]
	v_add_f32_e32 v0, 1.0, v0
	v_rcp_f32_e32 v68, v0
	v_mul_f32_e32 v0, 0xbfb8aa3b, v67
	v_exp_f32_e32 v0, v0
	s_nop 0
	v_add_f32_e32 v0, 1.0, v0
	v_rcp_f32_e32 v69, v0
	s_nop 0
	v_pk_mul_f32 v[58:59], v[68:69], v[66:67]
	s_nop 0
	v_pk_mul_f32 v[52:53], v[52:53], v[58:59]
	v_lshlrev_b32_e32 v58, 16, v221
	v_mul_f32_e32 v0, 0xbfb8aa3b, v58
	v_exp_f32_e32 v0, v0
	v_and_b32_e32 v59, 0xffff0000, v221
	v_cvt_pk_bf16_f32 v52, v52, v53
	v_add_f32_e32 v0, 1.0, v0
	v_rcp_f32_e32 v56, v0
	v_mul_f32_e32 v0, 0xbfb8aa3b, v59
	v_exp_f32_e32 v0, v0
	s_nop 0
	v_add_f32_e32 v0, 1.0, v0
	v_rcp_f32_e32 v57, v0
	s_nop 0
	v_pk_mul_f32 v[56:57], v[56:57], v[58:59]
	s_nop 0
	v_pk_mul_f32 v[54:55], v[54:55], v[56:57]
	s_nop 0
	v_cvt_pk_bf16_f32 v53, v54, v55
	global_store_dwordx2 v[50:51], v[52:53], off offset:32
	s_nop 0
	s_waitcnt vmcnt(28)
	v_lshlrev_b32_e32 v58, 16, v222
	v_mul_f32_e32 v0, 0xbfb8aa3b, v58
	v_exp_f32_e32 v0, v0
	v_and_b32_e32 v59, 0xffff0000, v222
	s_waitcnt vmcnt(27)
	v_pk_mul_f32 v[52:53], v[62:63], v[154:155]
	v_add_f32_e32 v0, 1.0, v0
	v_rcp_f32_e32 v60, v0
	v_mul_f32_e32 v0, 0xbfb8aa3b, v59
	v_exp_f32_e32 v0, v0
	s_nop 0
	v_add_f32_e32 v0, 1.0, v0
	v_rcp_f32_e32 v61, v0
	s_nop 0
	v_pk_mul_f32 v[58:59], v[60:61], v[58:59]
	s_nop 0
	v_pk_mul_f32 v[52:53], v[52:53], v[58:59]
	v_lshlrev_b32_e32 v58, 16, v223
	v_mul_f32_e32 v0, 0xbfb8aa3b, v58
	v_exp_f32_e32 v0, v0
	v_and_b32_e32 v59, 0xffff0000, v223
	v_pk_mul_f32 v[60:61], v[64:65], v[70:71] op_sel_hi:[1,0]
	v_cvt_pk_bf16_f32 v52, v52, v53
	v_add_f32_e32 v0, 1.0, v0
	v_rcp_f32_e32 v56, v0
	v_mul_f32_e32 v0, 0xbfb8aa3b, v59
	v_exp_f32_e32 v0, v0
	v_pk_mul_f32 v[54:55], v[60:61], v[156:157]
	v_add_f32_e32 v0, 1.0, v0
	v_rcp_f32_e32 v57, v0
	s_nop 0
	v_pk_mul_f32 v[56:57], v[56:57], v[58:59]
	s_nop 0
	v_pk_mul_f32 v[54:55], v[54:55], v[56:57]
	s_nop 0
	v_cvt_pk_bf16_f32 v53, v54, v55
	global_store_dwordx2 v[50:51], v[52:53], off offset:48
	s_nop 0
	s_waitcnt vmcnt(27)
	v_lshlrev_b32_e32 v58, 16, v224
	v_mul_f32_e32 v0, 0xbfb8aa3b, v58
	v_exp_f32_e32 v0, v0
	v_and_b32_e32 v59, 0xffff0000, v224
	s_waitcnt vmcnt(26)
	v_pk_mul_f32 v[34:35], v[34:35], v[158:159]
	v_pk_mul_f32 v[36:37], v[36:37], v[160:161]
	v_add_f32_e32 v0, 1.0, v0
	v_rcp_f32_e32 v60, v0
	v_mul_f32_e32 v0, 0xbfb8aa3b, v59
	v_exp_f32_e32 v0, v0
	s_nop 0
	v_add_f32_e32 v0, 1.0, v0
	v_rcp_f32_e32 v61, v0
	s_nop 0
	v_pk_mul_f32 v[52:53], v[60:61], v[58:59]
	s_nop 0
	v_pk_mul_f32 v[34:35], v[34:35], v[52:53]
	v_lshlrev_b32_e32 v52, 16, v225
	v_mul_f32_e32 v0, 0xbfb8aa3b, v52
	v_exp_f32_e32 v0, v0
	v_and_b32_e32 v53, 0xffff0000, v225
	v_cvt_pk_bf16_f32 v34, v34, v35
	v_add_f32_e32 v0, 1.0, v0
	v_rcp_f32_e32 v56, v0
	v_mul_f32_e32 v0, 0xbfb8aa3b, v53
	v_exp_f32_e32 v0, v0
	s_nop 0
	v_add_f32_e32 v0, 1.0, v0
	v_rcp_f32_e32 v57, v0
	s_nop 0
	v_pk_mul_f32 v[52:53], v[56:57], v[52:53]
	s_nop 0
	v_pk_mul_f32 v[36:37], v[36:37], v[52:53]
	s_nop 0
	v_cvt_pk_bf16_f32 v35, v36, v37
	global_store_dwordx2 v[50:51], v[34:35], off offset:64
	s_nop 0
	s_waitcnt vmcnt(26)
; DI float bf2f(bf16_t v) { return __uint_as_float(((unsigned)v) << 16); }
; DI float frcp(float x) { return __builtin_amdgcn_rcpf(x); }
; DI void st_bf16x4(bf16_t* p, f32x4 v) { u32x2 o; o.x = pk2e(v[0], v[1]); o.y = pk2e(v[2], v[3]); *(u32x2*)p = o; }
; DI void hgrn_out_task(const Params& p, int e, int bh, int c, int tt) {
;     ...
; #pragma unroll
;   for (int vt = 0; vt < 4; ++vt)
; #pragma unroll
;     for (int q = 0; q < 4; ++q) {
;       const int d0 = vt * 32 + q * 8 + 4 * g;
;       const s16x4 gv = *(const s16x4*)(hg + d0); const f32x4 gn = *(const f32x4*)(og + d0);
;       f32x4 v;
; #pragma unroll
;       for (int e2 = 0; e2 < 4; ++e2) { const float gg = bf2f((bf16_t)gv[e2]); v[e2] = o[vt][q * 4 + e2] * rs * gn[e2] * (gg * frcp(1.f + __expf(-gg))); }
;       st_bf16x4(orow + d0, v);
	v_lshlrev_b32_e32 v54, 16, v226
	v_mul_f32_e32 v0, 0xbfb8aa3b, v54
	v_exp_f32_e32 v0, v0
	v_and_b32_e32 v55, 0xffff0000, v226
	s_waitcnt vmcnt(25)
	v_pk_mul_f32 v[34:35], v[38:39], v[162:163]
	v_pk_mul_f32 v[36:37], v[40:41], v[164:165]
	v_add_f32_e32 v0, 1.0, v0
	v_rcp_f32_e32 v56, v0
	v_mul_f32_e32 v0, 0xbfb8aa3b, v55
	v_exp_f32_e32 v0, v0
	s_nop 0
	v_add_f32_e32 v0, 1.0, v0
	v_rcp_f32_e32 v57, v0
	s_nop 0
	v_pk_mul_f32 v[38:39], v[56:57], v[54:55]
	s_nop 0
	v_pk_mul_f32 v[34:35], v[34:35], v[38:39]
	v_lshlrev_b32_e32 v38, 16, v227
	v_mul_f32_e32 v0, 0xbfb8aa3b, v38
	v_exp_f32_e32 v0, v0
	v_and_b32_e32 v39, 0xffff0000, v227
	v_cvt_pk_bf16_f32 v34, v34, v35
	v_add_f32_e32 v0, 1.0, v0
	v_rcp_f32_e32 v52, v0
	v_mul_f32_e32 v0, 0xbfb8aa3b, v39
	v_exp_f32_e32 v0, v0
	s_nop 0
	v_add_f32_e32 v0, 1.0, v0
	v_rcp_f32_e32 v53, v0
	s_nop 0
	v_pk_mul_f32 v[38:39], v[52:53], v[38:39]
	s_nop 0
	v_pk_mul_f32 v[36:37], v[36:37], v[38:39]
	s_nop 0
	v_cvt_pk_bf16_f32 v35, v36, v37
	global_store_dwordx2 v[50:51], v[34:35], off offset:80
	s_nop 0
	s_waitcnt vmcnt(25)
	v_lshlrev_b32_e32 v40, 16, v228
	v_mul_f32_e32 v0, 0xbfb8aa3b, v40
	v_exp_f32_e32 v0, v0
	v_and_b32_e32 v41, 0xffff0000, v228
	s_waitcnt vmcnt(24)
	v_pk_mul_f32 v[34:35], v[42:43], v[166:167]
	v_pk_mul_f32 v[42:43], v[44:45], v[70:71] op_sel_hi:[1,0]
	v_add_f32_e32 v0, 1.0, v0
	v_rcp_f32_e32 v52, v0
	v_mul_f32_e32 v0, 0xbfb8aa3b, v41
	v_exp_f32_e32 v0, v0
	v_pk_mul_f32 v[36:37], v[42:43], v[168:169]
	v_pk_mul_f32 v[44:45], v[46:47], v[70:71] op_sel_hi:[1,0]
	v_add_f32_e32 v0, 1.0, v0
	v_rcp_f32_e32 v53, v0
	s_nop 0
	v_pk_mul_f32 v[40:41], v[52:53], v[40:41]
	s_nop 0
	v_pk_mul_f32 v[34:35], v[34:35], v[40:41]
	v_lshlrev_b32_e32 v40, 16, v229
	v_mul_f32_e32 v0, 0xbfb8aa3b, v40
	v_exp_f32_e32 v0, v0
	v_and_b32_e32 v41, 0xffff0000, v229
	v_cvt_pk_bf16_f32 v34, v34, v35
	v_add_f32_e32 v0, 1.0, v0
	v_rcp_f32_e32 v38, v0
	v_mul_f32_e32 v0, 0xbfb8aa3b, v41
	v_exp_f32_e32 v0, v0
	s_nop 0
	v_add_f32_e32 v0, 1.0, v0
	v_rcp_f32_e32 v39, v0
	s_nop 0
	v_pk_mul_f32 v[38:39], v[38:39], v[40:41]
	s_nop 0
	v_pk_mul_f32 v[36:37], v[36:37], v[38:39]
	s_nop 0
	v_cvt_pk_bf16_f32 v35, v36, v37
	global_store_dwordx2 v[50:51], v[34:35], off offset:96
	s_nop 0
	s_waitcnt vmcnt(24)
	v_lshlrev_b32_e32 v40, 16, v230
	v_mul_f32_e32 v0, 0xbfb8aa3b, v40
	v_exp_f32_e32 v0, v0
	v_and_b32_e32 v41, 0xffff0000, v230
	s_waitcnt vmcnt(23)
	v_pk_mul_f32 v[34:35], v[44:45], v[170:171]
	v_add_f32_e32 v0, 1.0, v0
	v_rcp_f32_e32 v42, v0
	v_mul_f32_e32 v0, 0xbfb8aa3b, v41
	v_exp_f32_e32 v0, v0
	s_nop 0
	v_add_f32_e32 v0, 1.0, v0
	v_rcp_f32_e32 v43, v0
	s_nop 0
	v_pk_mul_f32 v[40:41], v[42:43], v[40:41]
	s_nop 0
	v_pk_mul_f32 v[34:35], v[34:35], v[40:41]
	v_lshlrev_b32_e32 v40, 16, v231
	v_mul_f32_e32 v0, 0xbfb8aa3b, v40
	v_exp_f32_e32 v0, v0
	v_and_b32_e32 v41, 0xffff0000, v231
	v_pk_mul_f32 v[42:43], v[48:49], v[70:71] op_sel_hi:[1,0]
	v_cvt_pk_bf16_f32 v34, v34, v35
	v_add_f32_e32 v0, 1.0, v0
	v_rcp_f32_e32 v38, v0
	v_mul_f32_e32 v0, 0xbfb8aa3b, v41
	v_exp_f32_e32 v0, v0
	v_pk_mul_f32 v[36:37], v[42:43], v[172:173]
	v_add_f32_e32 v0, 1.0, v0
	v_rcp_f32_e32 v39, v0
	s_nop 0
	v_pk_mul_f32 v[38:39], v[38:39], v[40:41]
	s_nop 0
	v_pk_mul_f32 v[36:37], v[36:37], v[38:39]
	s_nop 0
	v_cvt_pk_bf16_f32 v35, v36, v37
	global_store_dwordx2 v[50:51], v[34:35], off offset:112
	s_nop 0
	s_waitcnt vmcnt(23)
	v_lshlrev_b32_e32 v40, 16, v232
	v_mul_f32_e32 v0, 0xbfb8aa3b, v40
	v_exp_f32_e32 v0, v0
	v_and_b32_e32 v41, 0xffff0000, v232
	s_waitcnt vmcnt(22)
	v_pk_mul_f32 v[18:19], v[18:19], v[174:175]
	v_pk_mul_f32 v[20:21], v[20:21], v[176:177]
	v_add_f32_e32 v0, 1.0, v0
	v_rcp_f32_e32 v42, v0
	v_mul_f32_e32 v0, 0xbfb8aa3b, v41
	v_exp_f32_e32 v0, v0
	s_nop 0
	v_add_f32_e32 v0, 1.0, v0
	v_rcp_f32_e32 v43, v0
	s_nop 0
	v_pk_mul_f32 v[34:35], v[42:43], v[40:41]
	s_nop 0
	v_pk_mul_f32 v[18:19], v[18:19], v[34:35]
	v_lshlrev_b32_e32 v34, 16, v233
	v_mul_f32_e32 v0, 0xbfb8aa3b, v34
	v_exp_f32_e32 v0, v0
	v_and_b32_e32 v35, 0xffff0000, v233
	v_cvt_pk_bf16_f32 v18, v18, v19
	v_add_f32_e32 v0, 1.0, v0
	v_rcp_f32_e32 v38, v0
	v_mul_f32_e32 v0, 0xbfb8aa3b, v35
	v_exp_f32_e32 v0, v0
	s_nop 0
	v_add_f32_e32 v0, 1.0, v0
	v_rcp_f32_e32 v39, v0
	s_nop 0
	v_pk_mul_f32 v[34:35], v[38:39], v[34:35]
	s_nop 0
	v_pk_mul_f32 v[20:21], v[20:21], v[34:35]
	s_nop 0
	v_cvt_pk_bf16_f32 v19, v20, v21
	global_store_dwordx2 v[50:51], v[18:19], off offset:128
	s_nop 0
	s_waitcnt vmcnt(22)
	v_lshlrev_b32_e32 v36, 16, v234
	v_mul_f32_e32 v0, 0xbfb8aa3b, v36
	v_exp_f32_e32 v0, v0
	v_and_b32_e32 v37, 0xffff0000, v234
	s_waitcnt vmcnt(21)
	v_pk_mul_f32 v[18:19], v[22:23], v[178:179]
	v_pk_mul_f32 v[20:21], v[24:25], v[180:181]
	v_add_f32_e32 v0, 1.0, v0
	v_rcp_f32_e32 v38, v0
	v_mul_f32_e32 v0, 0xbfb8aa3b, v37
	v_exp_f32_e32 v0, v0
	s_nop 0
	v_add_f32_e32 v0, 1.0, v0
	v_rcp_f32_e32 v39, v0
	s_nop 0
	v_pk_mul_f32 v[22:23], v[38:39], v[36:37]
	s_nop 0
	v_pk_mul_f32 v[18:19], v[18:19], v[22:23]
	v_lshlrev_b32_e32 v22, 16, v235
	v_mul_f32_e32 v0, 0xbfb8aa3b, v22
	v_exp_f32_e32 v0, v0
	v_and_b32_e32 v23, 0xffff0000, v235
	v_cvt_pk_bf16_f32 v18, v18, v19
	v_add_f32_e32 v0, 1.0, v0
	v_rcp_f32_e32 v34, v0
	v_mul_f32_e32 v0, 0xbfb8aa3b, v23
	v_exp_f32_e32 v0, v0
	s_nop 0
	v_add_f32_e32 v0, 1.0, v0
	v_rcp_f32_e32 v35, v0
	s_nop 0
	v_pk_mul_f32 v[22:23], v[34:35], v[22:23]
	s_nop 0
	v_pk_mul_f32 v[20:21], v[20:21], v[22:23]
	s_nop 0
	v_cvt_pk_bf16_f32 v19, v20, v21
	global_store_dwordx2 v[50:51], v[18:19], off offset:144
	s_nop 0
	s_waitcnt vmcnt(21)
	v_lshlrev_b32_e32 v24, 16, v236
	v_mul_f32_e32 v0, 0xbfb8aa3b, v24
	v_exp_f32_e32 v0, v0
	v_and_b32_e32 v25, 0xffff0000, v236
	s_waitcnt vmcnt(20)
; DI float bf2f(bf16_t v) { return __uint_as_float(((unsigned)v) << 16); }
; DI float frcp(float x) { return __builtin_amdgcn_rcpf(x); }
; DI void st_bf16x4(bf16_t* p, f32x4 v) { u32x2 o; o.x = pk2e(v[0], v[1]); o.y = pk2e(v[2], v[3]); *(u32x2*)p = o; }
; DI void hgrn_out_task(const Params& p, int e, int bh, int c, int tt) {
;     ...
; #pragma unroll
;   for (int vt = 0; vt < 4; ++vt)
; #pragma unroll
;     for (int q = 0; q < 4; ++q) {
;       const int d0 = vt * 32 + q * 8 + 4 * g;
;       const s16x4 gv = *(const s16x4*)(hg + d0); const f32x4 gn = *(const f32x4*)(og + d0);
;       f32x4 v;
; #pragma unroll
;       for (int e2 = 0; e2 < 4; ++e2) { const float gg = bf2f((bf16_t)gv[e2]); v[e2] = o[vt][q * 4 + e2] * rs * gn[e2] * (gg * frcp(1.f + __expf(-gg))); }
;       st_bf16x4(orow + d0, v);
	v_pk_mul_f32 v[18:19], v[26:27], v[182:183]
	v_pk_mul_f32 v[26:27], v[28:29], v[70:71] op_sel_hi:[1,0]
	v_add_f32_e32 v0, 1.0, v0
	v_rcp_f32_e32 v34, v0
	v_mul_f32_e32 v0, 0xbfb8aa3b, v25
	v_exp_f32_e32 v0, v0
	v_pk_mul_f32 v[20:21], v[26:27], v[184:185]
	v_pk_mul_f32 v[28:29], v[30:31], v[70:71] op_sel_hi:[1,0]
	v_add_f32_e32 v0, 1.0, v0
	v_rcp_f32_e32 v35, v0
	s_nop 0
	v_pk_mul_f32 v[24:25], v[34:35], v[24:25]
	s_nop 0
	v_pk_mul_f32 v[18:19], v[18:19], v[24:25]
	v_lshlrev_b32_e32 v24, 16, v237
	v_mul_f32_e32 v0, 0xbfb8aa3b, v24
	v_exp_f32_e32 v0, v0
	v_and_b32_e32 v25, 0xffff0000, v237
	v_cvt_pk_bf16_f32 v18, v18, v19
	v_add_f32_e32 v0, 1.0, v0
	v_rcp_f32_e32 v22, v0
	v_mul_f32_e32 v0, 0xbfb8aa3b, v25
	v_exp_f32_e32 v0, v0
	s_nop 0
	v_add_f32_e32 v0, 1.0, v0
	v_rcp_f32_e32 v23, v0
	s_nop 0
	v_pk_mul_f32 v[22:23], v[22:23], v[24:25]
	s_nop 0
	v_pk_mul_f32 v[20:21], v[20:21], v[22:23]
	s_nop 0
	v_cvt_pk_bf16_f32 v19, v20, v21
	global_store_dwordx2 v[50:51], v[18:19], off offset:160
	s_nop 0
	s_waitcnt vmcnt(20)
	v_lshlrev_b32_e32 v24, 16, v238
	v_mul_f32_e32 v0, 0xbfb8aa3b, v24
	v_exp_f32_e32 v0, v0
	v_and_b32_e32 v25, 0xffff0000, v238
	s_waitcnt vmcnt(19)
	v_pk_mul_f32 v[18:19], v[28:29], v[186:187]
	v_add_f32_e32 v0, 1.0, v0
	v_rcp_f32_e32 v26, v0
	v_mul_f32_e32 v0, 0xbfb8aa3b, v25
	v_exp_f32_e32 v0, v0
	s_nop 0
	v_add_f32_e32 v0, 1.0, v0
	v_rcp_f32_e32 v27, v0
	s_nop 0
	v_pk_mul_f32 v[24:25], v[26:27], v[24:25]
	s_nop 0
	v_pk_mul_f32 v[18:19], v[18:19], v[24:25]
	v_lshlrev_b32_e32 v24, 16, v239
	v_mul_f32_e32 v0, 0xbfb8aa3b, v24
	v_exp_f32_e32 v0, v0
	v_and_b32_e32 v25, 0xffff0000, v239
	v_pk_mul_f32 v[26:27], v[32:33], v[70:71] op_sel_hi:[1,0]
	v_cvt_pk_bf16_f32 v18, v18, v19
	v_add_f32_e32 v0, 1.0, v0
	v_rcp_f32_e32 v22, v0
	v_mul_f32_e32 v0, 0xbfb8aa3b, v25
	v_exp_f32_e32 v0, v0
	v_pk_mul_f32 v[20:21], v[26:27], v[188:189]
	v_add_f32_e32 v0, 1.0, v0
	v_rcp_f32_e32 v23, v0
	s_nop 0
	v_pk_mul_f32 v[22:23], v[22:23], v[24:25]
	s_nop 0
	v_pk_mul_f32 v[20:21], v[20:21], v[22:23]
	s_nop 0
	v_cvt_pk_bf16_f32 v19, v20, v21
	global_store_dwordx2 v[50:51], v[18:19], off offset:176
	s_nop 0
	s_waitcnt vmcnt(19)
	v_lshlrev_b32_e32 v24, 16, v240
	v_mul_f32_e32 v0, 0xbfb8aa3b, v24
	v_exp_f32_e32 v0, v0
	v_and_b32_e32 v25, 0xffff0000, v240
	s_waitcnt vmcnt(18)
	v_pk_mul_f32 v[2:3], v[2:3], v[200:201]
	v_pk_mul_f32 v[4:5], v[4:5], v[202:203]
	v_add_f32_e32 v0, 1.0, v0
	v_rcp_f32_e32 v26, v0
	v_mul_f32_e32 v0, 0xbfb8aa3b, v25
	v_exp_f32_e32 v0, v0
	s_nop 0
	v_add_f32_e32 v0, 1.0, v0
	v_rcp_f32_e32 v27, v0
	s_nop 0
	v_pk_mul_f32 v[18:19], v[26:27], v[24:25]
	s_nop 0
	v_pk_mul_f32 v[2:3], v[2:3], v[18:19]
	v_lshlrev_b32_e32 v18, 16, v241
	v_mul_f32_e32 v0, 0xbfb8aa3b, v18
	v_exp_f32_e32 v0, v0
	v_and_b32_e32 v19, 0xffff0000, v241
	v_cvt_pk_bf16_f32 v2, v2, v3
	v_add_f32_e32 v0, 1.0, v0
	v_rcp_f32_e32 v22, v0
	v_mul_f32_e32 v0, 0xbfb8aa3b, v19
	v_exp_f32_e32 v0, v0
	s_nop 0
	v_add_f32_e32 v0, 1.0, v0
	v_rcp_f32_e32 v23, v0
	s_nop 0
	v_pk_mul_f32 v[18:19], v[22:23], v[18:19]
	s_nop 0
	v_pk_mul_f32 v[4:5], v[4:5], v[18:19]
	s_nop 0
	v_cvt_pk_bf16_f32 v3, v4, v5
	global_store_dwordx2 v[50:51], v[2:3], off offset:192
	s_nop 0
	s_waitcnt vmcnt(18)
	v_lshlrev_b32_e32 v20, 16, v242
	v_mul_f32_e32 v0, 0xbfb8aa3b, v20
	v_exp_f32_e32 v0, v0
	v_and_b32_e32 v21, 0xffff0000, v242
	s_waitcnt vmcnt(17)
	v_pk_mul_f32 v[2:3], v[6:7], v[204:205]
	v_pk_mul_f32 v[4:5], v[8:9], v[206:207]
	v_add_f32_e32 v0, 1.0, v0
	v_rcp_f32_e32 v22, v0
	v_mul_f32_e32 v0, 0xbfb8aa3b, v21
	v_exp_f32_e32 v0, v0
	s_nop 0
	v_add_f32_e32 v0, 1.0, v0
	v_rcp_f32_e32 v23, v0
	s_nop 0
	v_pk_mul_f32 v[6:7], v[22:23], v[20:21]
	s_nop 0
	v_pk_mul_f32 v[2:3], v[2:3], v[6:7]
	v_lshlrev_b32_e32 v6, 16, v243
	v_mul_f32_e32 v0, 0xbfb8aa3b, v6
	v_exp_f32_e32 v0, v0
	v_and_b32_e32 v7, 0xffff0000, v243
	v_cvt_pk_bf16_f32 v2, v2, v3
	v_add_f32_e32 v0, 1.0, v0
	v_rcp_f32_e32 v18, v0
	v_mul_f32_e32 v0, 0xbfb8aa3b, v7
	v_exp_f32_e32 v0, v0
	s_nop 0
	v_add_f32_e32 v0, 1.0, v0
	v_rcp_f32_e32 v19, v0
	s_nop 0
	v_pk_mul_f32 v[6:7], v[18:19], v[6:7]
	s_nop 0
	v_pk_mul_f32 v[4:5], v[4:5], v[6:7]
	s_nop 0
	v_cvt_pk_bf16_f32 v3, v4, v5
	global_store_dwordx2 v[50:51], v[2:3], off offset:208
	s_nop 0
	s_waitcnt vmcnt(17)
	v_lshlrev_b32_e32 v8, 16, v244
	v_mul_f32_e32 v0, 0xbfb8aa3b, v8
	v_exp_f32_e32 v0, v0
	v_and_b32_e32 v9, 0xffff0000, v244
	s_waitcnt vmcnt(16)
	v_pk_mul_f32 v[2:3], v[10:11], v[208:209]
	v_pk_mul_f32 v[10:11], v[12:13], v[70:71] op_sel_hi:[1,0]
	v_add_f32_e32 v0, 1.0, v0
	v_rcp_f32_e32 v18, v0
	v_mul_f32_e32 v0, 0xbfb8aa3b, v9
	v_exp_f32_e32 v0, v0
	v_pk_mul_f32 v[4:5], v[10:11], v[210:211]
	v_pk_mul_f32 v[12:13], v[14:15], v[70:71] op_sel_hi:[1,0]
	v_add_f32_e32 v0, 1.0, v0
	v_rcp_f32_e32 v19, v0
	s_nop 0
	v_pk_mul_f32 v[8:9], v[18:19], v[8:9]
	s_nop 0
	v_pk_mul_f32 v[2:3], v[2:3], v[8:9]
	v_lshlrev_b32_e32 v8, 16, v245
	v_mul_f32_e32 v0, 0xbfb8aa3b, v8
	v_exp_f32_e32 v0, v0
	v_and_b32_e32 v9, 0xffff0000, v245
	v_cvt_pk_bf16_f32 v2, v2, v3
	v_add_f32_e32 v0, 1.0, v0
	v_rcp_f32_e32 v6, v0
	v_mul_f32_e32 v0, 0xbfb8aa3b, v9
	v_exp_f32_e32 v0, v0
	s_nop 0
	v_add_f32_e32 v0, 1.0, v0
	v_rcp_f32_e32 v7, v0
	s_nop 0
	v_pk_mul_f32 v[6:7], v[6:7], v[8:9]
	s_nop 0
	v_pk_mul_f32 v[4:5], v[4:5], v[6:7]
	s_nop 0
	v_cvt_pk_bf16_f32 v3, v4, v5
	global_store_dwordx2 v[50:51], v[2:3], off offset:224
	s_nop 0
	s_waitcnt vmcnt(16)
	v_lshlrev_b32_e32 v8, 16, v246
	v_mul_f32_e32 v0, 0xbfb8aa3b, v8
	v_exp_f32_e32 v0, v0
	v_and_b32_e32 v9, 0xffff0000, v246
	s_waitcnt vmcnt(15)
	v_pk_mul_f32 v[2:3], v[12:13], v[212:213]
	v_add_f32_e32 v0, 1.0, v0
	v_rcp_f32_e32 v10, v0
	v_mul_f32_e32 v0, 0xbfb8aa3b, v9
	v_exp_f32_e32 v0, v0
	s_nop 0
	v_add_f32_e32 v0, 1.0, v0
	v_rcp_f32_e32 v11, v0
	s_nop 0
	v_pk_mul_f32 v[8:9], v[10:11], v[8:9]
	s_nop 0
	v_pk_mul_f32 v[2:3], v[2:3], v[8:9]
	v_lshlrev_b32_e32 v8, 16, v247
	v_mul_f32_e32 v0, 0xbfb8aa3b, v8
	v_exp_f32_e32 v0, v0
	v_and_b32_e32 v9, 0xffff0000, v247
	v_pk_mul_f32 v[10:11], v[16:17], v[70:71] op_sel_hi:[1,0]
	v_cvt_pk_bf16_f32 v2, v2, v3
	v_add_f32_e32 v0, 1.0, v0
	v_rcp_f32_e32 v6, v0
	v_mul_f32_e32 v0, 0xbfb8aa3b, v9
	v_exp_f32_e32 v0, v0
	v_pk_mul_f32 v[4:5], v[10:11], v[214:215]
	v_add_f32_e32 v0, 1.0, v0
	v_rcp_f32_e32 v7, v0
	s_nop 0
	v_pk_mul_f32 v[6:7], v[6:7], v[8:9]
	s_nop 0
	v_pk_mul_f32 v[4:5], v[4:5], v[6:7]
	s_nop 0
	v_cvt_pk_bf16_f32 v3, v4, v5
	global_store_dwordx2 v[50:51], v[2:3], off offset:240
	s_andn2_b64 exec, exec, s[52:53]
	s_cbranch_execnz .LBB0_282
